# code placement: diff loop head aligned to 64 bytes (padding is unreachable, behind the prologue's branch)
# baseline (speedup 1.0000x reference)
; DI void diff_item(const Params& P, char* lds, int layer, int pair, int qt, int& tab_head) {
;     ...
;     const float cfar = tabg[2111];
;     const unsigned lds0 = (unsigned)(uintptr_t)lds;
;     int goff[2];
; #pragma unroll
;     for (int i = 0; i < 2; ++i) goff[i] = (8 * w + 4 * i + (lane >> 4)) * PO + (((lane & 15) ^ (((lane >> 4) << 2) | ((2 * w + i) & 3))) * 8);
;     const u16* kg = base + head * 128 + OFF_CK;
;     const u16* vg = base + head * 128 + OFF_CV;
;     auto issue = [&](int kt, int buf) {
;         const size_t to = (size_t)(64 * kt) * PO;
; #pragma unroll
;         for (int i = 0; i < 2; ++i) {
;             glds16(kg + to + goff[i], (unsigned)__builtin_amdgcn_readfirstlane(lds0 + buf * 32768 + (2 * w + i) * 1024));
;             glds16(vg + to + goff[i], (unsigned)__builtin_amdgcn_readfirstlane(lds0 + buf * 32768 + 16384 + (2 * w + i) * 1024));
;         }
;     };
;     issue(0, 0);
;     bf16x8 qf[4];
; #pragma unroll
;     for (int s = 0; s < 4; ++s) qf[s] = *(const bf16x8*)(base + (size_t)qpos * PO + OFF_CQ + head * 128 + mp * 64 + 16 * s + 8 * hh);
;     float m = -1e30f, l = 0.f;
;     f32x16 O[4];
; #pragma unroll
;     for (int dt = 0; dt < 4; ++dt)
; #pragma unroll
;         for (int i = 0; i < 16; ++i) O[dt][i] = 0.f;
;     const int sig_r = ((r & 3) << 2) | ((r >> 2) & 3);
;     const int kx0 = (8 * mp + hh) ^ sig_r;
;     const int i16 = lane & 15, q = i16 >> 2, pp = i16 & 3, blk = (lane >> 4) & 1;
;     const int vl0 = (4 * hh + q) * 256 + (16 * ((q << 2) | (blk << 1) | ((pp >> 1) ^ hh)) + 8 * (pp & 1));
;     const int nkt = 2 * qt + 2;
.LBB0_250:
	s_or_b64 exec, exec, s[0:1]
	v_ashrrev_i32_e32 v169, 6, v168
	v_mov_b64_e32 v[2:3], s[20:21]
	s_waitcnt vmcnt(0)
	flat_load_dword v198, v[2:3]
	v_bfe_u32 v2, v168, 4, 2
	v_lshlrev_b32_e32 v7, 1, v169
	v_lshl_or_b32 v3, v169, 3, v2
	v_lshlrev_b32_e32 v2, 2, v2
	v_and_b32_e32 v7, 2, v7
	v_and_b32_e32 v6, 15, v168
	v_or_b32_e32 v9, v7, v2
	v_mul_lo_u32 v3, v3, s67
	v_bitop3_b32 v2, v7, v6, v2 bitop3:0x36
	v_bitop3_b32 v6, v9, v6, 1 bitop3:0x36
	v_lshl_or_b32 v2, v2, 3, v3
	v_lshlrev_b32_e32 v6, 3, v6
	s_sub_i32 s22, 63, s25
	v_add3_u32 v6, v3, v6, s43
	v_ashrrev_i32_e32 v3, 31, v2
	v_lshlrev_b64 v[170:171], 1, v[2:3]
	v_lshlrev_b32_e32 v9, 11, v169
	s_cmp_lg_u32 0, -1
	v_lshl_add_u64 v[2:3], s[96:97], 0, v[170:171]
	v_readfirstlane_b32 s0, v9
	s_cselect_b32 s23, 0, 0
	v_ashrrev_i32_e32 v7, 31, v6
	v_and_b32_e32 v194, 3, v169
	s_add_i32 s1, s0, s23
	s_mov_b32 s16, m0
	s_mov_b32 m0, s1
	s_nop 0
	global_load_lds_dwordx4 v[2:3], off
	s_mov_b32 m0, s16
	v_lshl_add_u64 v[2:3], s[14:15], 0, v[170:171]
	s_add_i32 s40, s23, 0x4000
	v_lshlrev_b64 v[172:173], 1, v[6:7]
	v_lshlrev_b32_e32 v5, 5, v194
	s_add_i32 s1, s0, s40
	s_mov_b32 s16, m0
	s_mov_b32 m0, s1
	s_nop 0
	global_load_lds_dwordx4 v[2:3], off
	s_mov_b32 m0, s16
	v_lshl_add_u64 v[2:3], s[96:97], 0, v[172:173]
	s_add_i32 s41, s23, 0x400
	v_and_b32_e32 v195, 31, v168
	v_lshl_or_b32 v8, s22, 7, v5
	s_add_i32 s1, s0, s41
	s_mov_b32 s16, m0
	s_mov_b32 m0, s1
	s_nop 0
	global_load_lds_dwordx4 v[2:3], off
	s_mov_b32 m0, s16
	v_lshl_add_u64 v[2:3], s[14:15], 0, v[172:173]
	s_add_i32 s51, s23, 0x4400
	v_or_b32_e32 v0, v8, v195
	s_add_i32 s0, s0, s51
	s_mov_b32 s1, m0
	s_mov_b32 m0, s0
	s_nop 0
	global_load_lds_dwordx4 v[2:3], off
	s_mov_b32 m0, s1
	v_mov_b64_e32 v[2:3], s[58:59]
	v_mad_u64_u32 v[166:167], s[0:1], v0, s52, v[2:3]
	s_lshl_b32 s16, s24, 1
	v_ashrrev_i32_e32 v197, 8, v168
	v_lshl_add_u64 v[2:3], v[166:167], 0, s[16:17]
	s_mov_b64 s[0:1], 0x1b00
	v_lshl_add_u64 v[164:165], v[2:3], 0, s[0:1]
	v_lshlrev_b32_e32 v2, 6, v197
	v_bfe_u32 v196, v168, 5, 1
	v_ashrrev_i32_e32 v3, 31, v2
	v_lshl_add_u64 v[2:3], v[2:3], 1, v[164:165]
	v_lshlrev_b32_e32 v0, 4, v196
	v_lshl_add_u64 v[2:3], v[2:3], 0, v[0:1]
	flat_load_dwordx4 v[144:147], v[2:3]
	flat_load_dwordx4 v[148:151], v[2:3] offset:32
	flat_load_dwordx4 v[152:155], v[2:3] offset:64
	flat_load_dwordx4 v[156:159], v[2:3] offset:96
	v_bfe_u32 v2, v168, 2, 2
	v_and_or_b32 v3, v4, 12, v2
	v_lshlrev_b32_e32 v4, 3, v197
	v_lshlrev_b32_e32 v193, 2, v196
	v_lshrrev_b32_e32 v6, 3, v168
	v_lshrrev_b32_e32 v7, 1, v168
	v_bitop3_b32 v3, v4, v3, v196 bitop3:0x36
	v_or_b32_e32 v4, v193, v2
	v_lshlrev_b32_e32 v2, 2, v2
	v_and_b32_e32 v6, 2, v6
	v_bitop3_b32 v7, v7, v196, 1 bitop3:0x6c
	v_or3_b32 v2, v2, v6, v7
	v_lshlrev_b32_e32 v6, 3, v168
	v_and_b32_e32 v6, 8, v6
	v_lshlrev_b32_e32 v4, 8, v4
	v_lshl_or_b32 v2, v2, 4, v6
	s_movk_i32 s0, 0x60
	v_bitop3_b32 v212, v2, s0, v4 bitop3:0x36
	s_movk_i32 s0, 0x80
	v_bitop3_b32 v213, v2, s0, v4 bitop3:0x36
	s_movk_i32 s0, 0xa0
	v_bitop3_b32 v214, v2, s0, v4 bitop3:0x36
	s_movk_i32 s0, 0xc0
	v_bitop3_b32 v215, v2, s0, v4 bitop3:0x36
	s_movk_i32 s0, 0xe0
	v_bitop3_b32 v216, v2, s0, v4 bitop3:0x36
	s_lshl_b32 s0, s25, 7
	v_or_b32_e32 v199, v2, v4
	v_bitop3_b32 v210, v2, 32, v4 bitop3:0x36
	v_bitop3_b32 v211, v2, 64, v4 bitop3:0x36
	v_subrev_u32_e32 v2, s0, v5
	v_add_u32_e32 v217, 0x1f41, v2
	v_lshlrev_b32_e32 v2, 2, v195
	v_lshl_or_b32 v2, v194, 7, v2
	v_sub_u32_e32 v0, v2, v0
	s_lshl_b32 s0, s25, 9
	s_lshl_b32 s49, s22, 1
	v_lshlrev_b32_e32 v6, 8, v168
	v_subrev_u32_e32 v0, s0, v0
	s_add_i32 s0, 0, 0x27e14
	v_mov_b32_e32 v14, v1
	v_mov_b32_e32 v15, v1
	s_add_i32 s49, s49, 2
	v_or_b32_e32 v200, 31, v8
	v_and_b32_e32 v201, 0x1f00, v6
	v_lshlrev_b32_e32 v202, 4, v3
	v_add_u32_e32 v206, s23, v9
	v_add_u32_e32 v207, s40, v9
	v_add_u32_e32 v208, s41, v9
	v_add_u32_e32 v209, s51, v9
	v_add_u32_e32 v218, s0, v0
	v_mov_b32_e32 v0, v1
	v_mov_b32_e32 v2, v1
	v_mov_b32_e32 v3, v1
	v_mov_b32_e32 v4, v1
	v_mov_b32_e32 v5, v1
	v_mov_b32_e32 v6, v1
	v_mov_b32_e32 v7, v1
	v_mov_b32_e32 v8, v1
	v_mov_b32_e32 v9, v1
	v_mov_b32_e32 v10, v1
	v_mov_b32_e32 v11, v1
	v_mov_b32_e32 v12, v1
	v_mov_b32_e32 v13, v1
	v_mov_b64_e32 v[30:31], v[14:15]
	v_mov_b64_e32 v[46:47], v[14:15]
	v_mov_b64_e32 v[62:63], v[14:15]
	v_mov_b64_e32 v[78:79], v[14:15]
	v_xor_b32_e32 v203, 32, v202
	s_mov_b32 s50, 64
	v_xor_b32_e32 v204, 64, v202
	v_xor_b32_e32 v205, 0x60, v202
	s_max_u32 s51, s49, 1
	v_mov_b32_e32 v219, 0
	v_mov_b32_e32 v226, 0xf149f2ca
	s_mov_b32 s25, 0x8000
	v_mov_b32_e32 v220, 0
	s_mov_b64 s[0:1], 0
	v_mov_b64_e32 v[28:29], v[12:13]
	v_mov_b64_e32 v[26:27], v[10:11]
	v_mov_b64_e32 v[24:25], v[8:9]
	v_mov_b64_e32 v[22:23], v[6:7]
	v_mov_b64_e32 v[20:21], v[4:5]
	v_mov_b64_e32 v[18:19], v[2:3]
	v_mov_b64_e32 v[16:17], v[0:1]
	v_mov_b64_e32 v[44:45], v[12:13]
	v_mov_b64_e32 v[42:43], v[10:11]
	v_mov_b64_e32 v[40:41], v[8:9]
	v_mov_b64_e32 v[38:39], v[6:7]
	v_mov_b64_e32 v[36:37], v[4:5]
	v_mov_b64_e32 v[34:35], v[2:3]
	v_mov_b64_e32 v[32:33], v[0:1]
	v_mov_b64_e32 v[60:61], v[12:13]
	v_mov_b64_e32 v[58:59], v[10:11]
	v_mov_b64_e32 v[56:57], v[8:9]
	v_mov_b64_e32 v[54:55], v[6:7]
	v_mov_b64_e32 v[52:53], v[4:5]
	v_mov_b64_e32 v[50:51], v[2:3]
	v_mov_b64_e32 v[48:49], v[0:1]
	v_mov_b64_e32 v[76:77], v[12:13]
	v_mov_b64_e32 v[74:75], v[10:11]
	v_mov_b64_e32 v[72:73], v[8:9]
	v_mov_b64_e32 v[70:71], v[6:7]
	v_mov_b64_e32 v[68:69], v[4:5]
	v_mov_b64_e32 v[66:67], v[2:3]
	v_mov_b64_e32 v[64:65], v[0:1]
	v_readfirstlane_b32 s63, v206
	s_add_u32 s64, s96, 0xe0000
	s_addc_u32 s65, s97, 0
	s_add_u32 s70, s14, 0xe0000
	s_addc_u32 s71, s15, 0
	s_mov_b32 s73, m0
	v_add_u32_e32 v14, v201, v202
	v_add_u32_e32 v15, v201, v203
	v_add_u32_e32 v221, v201, v204
	v_add_u32_e32 v222, v201, v205
	s_branch .Ldu_A
	.p2align	6
